# compact hand-written in-proj epilogue also for the silu*scale panels
# speedup vs baseline: 1.0252x; 1.0060x over previous
.LBB0_272:
	s_lshl_b32 s100, 1, s49
	s_and_b32 s101, s100, 0x1fa0
	s_cbranch_scc1 .Lepi_raw
	s_and_b32 s101, s100, 0x604c
	s_cbranch_scc1 .Lepi_silu
	s_branch .Lepi_std
.Lepi_raw:
	s_and_b32 s101, s100, 0x180
	s_cselect_b32 s101, 0x3e38aa3b, 1.0
	v_mul_f32_e32 v172, s101, v172
	v_mul_f32_e32 v170, s101, v170
	v_mul_f32_e32 v168, s101, v168
	v_mul_f32_e32 v166, s101, v166
	v_mul_f32_e32 v162, s101, v162
	v_mul_f32_e32 v160, s101, v160
	v_mul_f32_e32 v158, s101, v158
	v_mul_f32_e32 v156, s101, v156
	v_mov_b64_e32 v[128:129], s[50:51]
	v_mad_u64_u32 v[128:129], s[100:101], v174, s70, v[128:129]
	s_lshl_b32 s100, s49, 9
	s_nop 0
	v_lshl_add_u32 v190, v144, 1, s100
	v_lshl_add_u64 v[128:129], v[128:129], 0, v[190:191]
	s_mov_b64 s[100:101], 0x1e000
	v_mul_f32_e32 v60, v60, v172
	v_mul_f32_e32 v61, v61, v172
	v_mul_f32_e32 v62, v62, v172
	v_mul_f32_e32 v63, v63, v172
	v_mul_f32_e32 v56, v56, v172
	v_mul_f32_e32 v57, v57, v172
	v_mul_f32_e32 v58, v58, v172
	v_mul_f32_e32 v59, v59, v172
	v_cvt_pk_bf16_f32 v60, v60, v61
	v_cvt_pk_bf16_f32 v61, v62, v63
	v_cvt_pk_bf16_f32 v62, v56, v57
	v_cvt_pk_bf16_f32 v63, v58, v59
	global_store_dwordx4 v[128:129], v[60:63], off
	v_mul_f32_e32 v124, v124, v172
	v_mul_f32_e32 v125, v125, v172
	v_mul_f32_e32 v126, v126, v172
	v_mul_f32_e32 v127, v127, v172
	v_mul_f32_e32 v120, v120, v172
	v_mul_f32_e32 v121, v121, v172
	v_mul_f32_e32 v122, v122, v172
	v_mul_f32_e32 v123, v123, v172
	v_cvt_pk_bf16_f32 v124, v124, v125
	v_cvt_pk_bf16_f32 v125, v126, v127
	v_cvt_pk_bf16_f32 v126, v120, v121
	v_cvt_pk_bf16_f32 v127, v122, v123
	global_store_dwordx4 v[128:129], v[124:127], off offset:256
	v_lshl_add_u64 v[128:129], v[128:129], 0, s[100:101]
	v_mul_f32_e32 v52, v52, v170
	v_mul_f32_e32 v53, v53, v170
	v_mul_f32_e32 v54, v54, v170
	v_mul_f32_e32 v55, v55, v170
	v_mul_f32_e32 v48, v48, v170
	v_mul_f32_e32 v49, v49, v170
	v_mul_f32_e32 v50, v50, v170
	v_mul_f32_e32 v51, v51, v170
	v_cvt_pk_bf16_f32 v52, v52, v53
	v_cvt_pk_bf16_f32 v53, v54, v55
	v_cvt_pk_bf16_f32 v54, v48, v49
	v_cvt_pk_bf16_f32 v55, v50, v51
	global_store_dwordx4 v[128:129], v[52:55], off
	v_mul_f32_e32 v116, v116, v170
	v_mul_f32_e32 v117, v117, v170
	v_mul_f32_e32 v118, v118, v170
	v_mul_f32_e32 v119, v119, v170
	v_mul_f32_e32 v112, v112, v170
	v_mul_f32_e32 v113, v113, v170
	v_mul_f32_e32 v114, v114, v170
	v_mul_f32_e32 v115, v115, v170
	v_cvt_pk_bf16_f32 v116, v116, v117
	v_cvt_pk_bf16_f32 v117, v118, v119
	v_cvt_pk_bf16_f32 v118, v112, v113
	v_cvt_pk_bf16_f32 v119, v114, v115
	global_store_dwordx4 v[128:129], v[116:119], off offset:256
	v_lshl_add_u64 v[128:129], v[128:129], 0, s[100:101]
	v_mul_f32_e32 v44, v44, v168
	v_mul_f32_e32 v45, v45, v168
	v_mul_f32_e32 v46, v46, v168
	v_mul_f32_e32 v47, v47, v168
	v_mul_f32_e32 v40, v40, v168
	v_mul_f32_e32 v41, v41, v168
	v_mul_f32_e32 v42, v42, v168
	v_mul_f32_e32 v43, v43, v168
	v_cvt_pk_bf16_f32 v44, v44, v45
	v_cvt_pk_bf16_f32 v45, v46, v47
	v_cvt_pk_bf16_f32 v46, v40, v41
	v_cvt_pk_bf16_f32 v47, v42, v43
	global_store_dwordx4 v[128:129], v[44:47], off
	v_mul_f32_e32 v108, v108, v168
	v_mul_f32_e32 v109, v109, v168
	v_mul_f32_e32 v110, v110, v168
	v_mul_f32_e32 v111, v111, v168
	v_mul_f32_e32 v104, v104, v168
	v_mul_f32_e32 v105, v105, v168
	v_mul_f32_e32 v106, v106, v168
	v_mul_f32_e32 v107, v107, v168
	v_cvt_pk_bf16_f32 v108, v108, v109
	v_cvt_pk_bf16_f32 v109, v110, v111
	v_cvt_pk_bf16_f32 v110, v104, v105
	v_cvt_pk_bf16_f32 v111, v106, v107
	global_store_dwordx4 v[128:129], v[108:111], off offset:256
	v_lshl_add_u64 v[128:129], v[128:129], 0, s[100:101]
	v_mul_f32_e32 v36, v36, v166
	v_mul_f32_e32 v37, v37, v166
	v_mul_f32_e32 v38, v38, v166
	v_mul_f32_e32 v39, v39, v166
	v_mul_f32_e32 v32, v32, v166
	v_mul_f32_e32 v33, v33, v166
	v_mul_f32_e32 v34, v34, v166
	v_mul_f32_e32 v35, v35, v166
	v_cvt_pk_bf16_f32 v36, v36, v37
	v_cvt_pk_bf16_f32 v37, v38, v39
	v_cvt_pk_bf16_f32 v38, v32, v33
	v_cvt_pk_bf16_f32 v39, v34, v35
	global_store_dwordx4 v[128:129], v[36:39], off
	v_mul_f32_e32 v100, v100, v166
	v_mul_f32_e32 v101, v101, v166
	v_mul_f32_e32 v102, v102, v166
	v_mul_f32_e32 v103, v103, v166
	v_mul_f32_e32 v96, v96, v166
	v_mul_f32_e32 v97, v97, v166
	v_mul_f32_e32 v98, v98, v166
	v_mul_f32_e32 v99, v99, v166
	v_cvt_pk_bf16_f32 v100, v100, v101
	v_cvt_pk_bf16_f32 v101, v102, v103
	v_cvt_pk_bf16_f32 v102, v96, v97
	v_cvt_pk_bf16_f32 v103, v98, v99
	global_store_dwordx4 v[128:129], v[100:103], off offset:256
	s_mov_b64 s[100:101], 0x96000
	v_lshl_add_u64 v[128:129], v[128:129], 0, s[100:101]
	s_mov_b64 s[100:101], 0x1e000
	v_mul_f32_e32 v28, v28, v162
	v_mul_f32_e32 v29, v29, v162
	v_mul_f32_e32 v30, v30, v162
	v_mul_f32_e32 v31, v31, v162
	v_mul_f32_e32 v24, v24, v162
	v_mul_f32_e32 v25, v25, v162
	v_mul_f32_e32 v26, v26, v162
	v_mul_f32_e32 v27, v27, v162
	v_cvt_pk_bf16_f32 v28, v28, v29
	v_cvt_pk_bf16_f32 v29, v30, v31
	v_cvt_pk_bf16_f32 v30, v24, v25
	v_cvt_pk_bf16_f32 v31, v26, v27
	global_store_dwordx4 v[128:129], v[28:31], off
	v_mul_f32_e32 v92, v92, v162
	v_mul_f32_e32 v93, v93, v162
	v_mul_f32_e32 v94, v94, v162
	v_mul_f32_e32 v95, v95, v162
	v_mul_f32_e32 v88, v88, v162
	v_mul_f32_e32 v89, v89, v162
	v_mul_f32_e32 v90, v90, v162
	v_mul_f32_e32 v91, v91, v162
	v_cvt_pk_bf16_f32 v92, v92, v93
	v_cvt_pk_bf16_f32 v93, v94, v95
	v_cvt_pk_bf16_f32 v94, v88, v89
	v_cvt_pk_bf16_f32 v95, v90, v91
	global_store_dwordx4 v[128:129], v[92:95], off offset:256
	v_lshl_add_u64 v[128:129], v[128:129], 0, s[100:101]
	v_mul_f32_e32 v20, v20, v160
	v_mul_f32_e32 v21, v21, v160
	v_mul_f32_e32 v22, v22, v160
	v_mul_f32_e32 v23, v23, v160
	v_mul_f32_e32 v16, v16, v160
	v_mul_f32_e32 v17, v17, v160
	v_mul_f32_e32 v18, v18, v160
	v_mul_f32_e32 v19, v19, v160
	v_cvt_pk_bf16_f32 v20, v20, v21
	v_cvt_pk_bf16_f32 v21, v22, v23
	v_cvt_pk_bf16_f32 v22, v16, v17
	v_cvt_pk_bf16_f32 v23, v18, v19
	global_store_dwordx4 v[128:129], v[20:23], off
	v_mul_f32_e32 v84, v84, v160
	v_mul_f32_e32 v85, v85, v160
	v_mul_f32_e32 v86, v86, v160
	v_mul_f32_e32 v87, v87, v160
	v_mul_f32_e32 v80, v80, v160
	v_mul_f32_e32 v81, v81, v160
	v_mul_f32_e32 v82, v82, v160
	v_mul_f32_e32 v83, v83, v160
	v_cvt_pk_bf16_f32 v84, v84, v85
	v_cvt_pk_bf16_f32 v85, v86, v87
	v_cvt_pk_bf16_f32 v86, v80, v81
	v_cvt_pk_bf16_f32 v87, v82, v83
	global_store_dwordx4 v[128:129], v[84:87], off offset:256
	v_lshl_add_u64 v[128:129], v[128:129], 0, s[100:101]
	v_mul_f32_e32 v12, v12, v158
	v_mul_f32_e32 v13, v13, v158
	v_mul_f32_e32 v14, v14, v158
	v_mul_f32_e32 v15, v15, v158
	v_mul_f32_e32 v8, v8, v158
	v_mul_f32_e32 v9, v9, v158
	v_mul_f32_e32 v10, v10, v158
	v_mul_f32_e32 v11, v11, v158
	v_cvt_pk_bf16_f32 v12, v12, v13
	v_cvt_pk_bf16_f32 v13, v14, v15
	v_cvt_pk_bf16_f32 v14, v8, v9
	v_cvt_pk_bf16_f32 v15, v10, v11
	global_store_dwordx4 v[128:129], v[12:15], off
	v_mul_f32_e32 v76, v76, v158
	v_mul_f32_e32 v77, v77, v158
	v_mul_f32_e32 v78, v78, v158
	v_mul_f32_e32 v79, v79, v158
	v_mul_f32_e32 v72, v72, v158
	v_mul_f32_e32 v73, v73, v158
	v_mul_f32_e32 v74, v74, v158
	v_mul_f32_e32 v75, v75, v158
	v_cvt_pk_bf16_f32 v76, v76, v77
	v_cvt_pk_bf16_f32 v77, v78, v79
	v_cvt_pk_bf16_f32 v78, v72, v73
	v_cvt_pk_bf16_f32 v79, v74, v75
	global_store_dwordx4 v[128:129], v[76:79], off offset:256
	v_lshl_add_u64 v[128:129], v[128:129], 0, s[100:101]
	v_mul_f32_e32 v4, v4, v156
	v_mul_f32_e32 v5, v5, v156
	v_mul_f32_e32 v6, v6, v156
	v_mul_f32_e32 v7, v7, v156
	v_mul_f32_e32 v0, v0, v156
	v_mul_f32_e32 v1, v1, v156
	v_mul_f32_e32 v2, v2, v156
	v_mul_f32_e32 v3, v3, v156
	v_cvt_pk_bf16_f32 v4, v4, v5
	v_cvt_pk_bf16_f32 v5, v6, v7
	v_cvt_pk_bf16_f32 v6, v0, v1
	v_cvt_pk_bf16_f32 v7, v2, v3
	global_store_dwordx4 v[128:129], v[4:7], off
	v_mul_f32_e32 v68, v68, v156
	v_mul_f32_e32 v69, v69, v156
	v_mul_f32_e32 v70, v70, v156
	v_mul_f32_e32 v71, v71, v156
	v_mul_f32_e32 v64, v64, v156
	v_mul_f32_e32 v65, v65, v156
	v_mul_f32_e32 v66, v66, v156
	v_mul_f32_e32 v67, v67, v156
	v_cvt_pk_bf16_f32 v68, v68, v69
	v_cvt_pk_bf16_f32 v69, v70, v71
	v_cvt_pk_bf16_f32 v70, v64, v65
	v_cvt_pk_bf16_f32 v71, v66, v67
	global_store_dwordx4 v[128:129], v[68:71], off offset:256
	s_branch .LBB0_271
.Lepi_silu:
	s_cmp_eq_u32 s49, 3
	s_cselect_b32 s101, 0x3e000000, 1.0
	v_mov_b32_e32 v210, s101
	v_mov_b64_e32 v[128:129], s[50:51]
	v_mad_u64_u32 v[128:129], s[100:101], v174, s70, v[128:129]
	s_lshl_b32 s100, s49, 9
	s_nop 0
	v_lshl_add_u32 v190, v144, 1, s100
	v_lshl_add_u64 v[128:129], v[128:129], 0, v[190:191]
	s_mov_b64 s[100:101], 0x1e000
	v_mul_f32_e32 v60, v60, v172
	v_mul_f32_e32 v61, v61, v172
	v_mul_f32_e32 v62, v62, v172
	v_mul_f32_e32 v63, v63, v172
	v_mul_f32_e32 v56, v56, v172
	v_mul_f32_e32 v57, v57, v172
	v_mul_f32_e32 v58, v58, v172
	v_mul_f32_e32 v59, v59, v172
	v_mul_f32_e32 v202, 0xbfb8aa3b, v60
	v_mul_f32_e32 v203, 0xbfb8aa3b, v61
	v_mul_f32_e32 v204, 0xbfb8aa3b, v62
	v_mul_f32_e32 v205, 0xbfb8aa3b, v63
	v_mul_f32_e32 v206, 0xbfb8aa3b, v56
	v_mul_f32_e32 v207, 0xbfb8aa3b, v57
	v_mul_f32_e32 v208, 0xbfb8aa3b, v58
	v_mul_f32_e32 v209, 0xbfb8aa3b, v59
	v_exp_f32_e32 v202, v202
	v_exp_f32_e32 v203, v203
	v_exp_f32_e32 v204, v204
	v_exp_f32_e32 v205, v205
	v_exp_f32_e32 v206, v206
	v_exp_f32_e32 v207, v207
	v_exp_f32_e32 v208, v208
	v_exp_f32_e32 v209, v209
	v_add_f32_e32 v202, 1.0, v202
	v_add_f32_e32 v203, 1.0, v203
	v_add_f32_e32 v204, 1.0, v204
	v_add_f32_e32 v205, 1.0, v205
	v_add_f32_e32 v206, 1.0, v206
	v_add_f32_e32 v207, 1.0, v207
	v_add_f32_e32 v208, 1.0, v208
	v_add_f32_e32 v209, 1.0, v209
	v_rcp_f32_e32 v202, v202
	v_rcp_f32_e32 v203, v203
	v_rcp_f32_e32 v204, v204
	v_rcp_f32_e32 v205, v205
	v_rcp_f32_e32 v206, v206
	v_rcp_f32_e32 v207, v207
	v_rcp_f32_e32 v208, v208
	v_rcp_f32_e32 v209, v209
	v_mul_f32_e32 v60, v60, v202
	v_mul_f32_e32 v61, v61, v203
	v_mul_f32_e32 v62, v62, v204
	v_mul_f32_e32 v63, v63, v205
	v_mul_f32_e32 v56, v56, v206
	v_mul_f32_e32 v57, v57, v207
	v_mul_f32_e32 v58, v58, v208
	v_mul_f32_e32 v59, v59, v209
	v_mul_f32_e32 v60, v210, v60
	v_mul_f32_e32 v61, v210, v61
	v_mul_f32_e32 v62, v210, v62
	v_mul_f32_e32 v63, v210, v63
	v_mul_f32_e32 v56, v210, v56
	v_mul_f32_e32 v57, v210, v57
	v_mul_f32_e32 v58, v210, v58
	v_mul_f32_e32 v59, v210, v59
	v_cvt_pk_bf16_f32 v60, v60, v61
	v_cvt_pk_bf16_f32 v61, v62, v63
	v_cvt_pk_bf16_f32 v62, v56, v57
	v_cvt_pk_bf16_f32 v63, v58, v59
	global_store_dwordx4 v[128:129], v[60:63], off
	v_mul_f32_e32 v124, v124, v172
	v_mul_f32_e32 v125, v125, v172
	v_mul_f32_e32 v126, v126, v172
	v_mul_f32_e32 v127, v127, v172
	v_mul_f32_e32 v120, v120, v172
	v_mul_f32_e32 v121, v121, v172
	v_mul_f32_e32 v122, v122, v172
	v_mul_f32_e32 v123, v123, v172
	v_mul_f32_e32 v202, 0xbfb8aa3b, v124
	v_mul_f32_e32 v203, 0xbfb8aa3b, v125
	v_mul_f32_e32 v204, 0xbfb8aa3b, v126
	v_mul_f32_e32 v205, 0xbfb8aa3b, v127
	v_mul_f32_e32 v206, 0xbfb8aa3b, v120
	v_mul_f32_e32 v207, 0xbfb8aa3b, v121
	v_mul_f32_e32 v208, 0xbfb8aa3b, v122
	v_mul_f32_e32 v209, 0xbfb8aa3b, v123
	v_exp_f32_e32 v202, v202
	v_exp_f32_e32 v203, v203
	v_exp_f32_e32 v204, v204
	v_exp_f32_e32 v205, v205
	v_exp_f32_e32 v206, v206
	v_exp_f32_e32 v207, v207
	v_exp_f32_e32 v208, v208
	v_exp_f32_e32 v209, v209
	v_add_f32_e32 v202, 1.0, v202
	v_add_f32_e32 v203, 1.0, v203
	v_add_f32_e32 v204, 1.0, v204
	v_add_f32_e32 v205, 1.0, v205
	v_add_f32_e32 v206, 1.0, v206
	v_add_f32_e32 v207, 1.0, v207
	v_add_f32_e32 v208, 1.0, v208
	v_add_f32_e32 v209, 1.0, v209
	v_rcp_f32_e32 v202, v202
	v_rcp_f32_e32 v203, v203
	v_rcp_f32_e32 v204, v204
	v_rcp_f32_e32 v205, v205
	v_rcp_f32_e32 v206, v206
	v_rcp_f32_e32 v207, v207
	v_rcp_f32_e32 v208, v208
	v_rcp_f32_e32 v209, v209
	v_mul_f32_e32 v124, v124, v202
	v_mul_f32_e32 v125, v125, v203
	v_mul_f32_e32 v126, v126, v204
	v_mul_f32_e32 v127, v127, v205
	v_mul_f32_e32 v120, v120, v206
	v_mul_f32_e32 v121, v121, v207
	v_mul_f32_e32 v122, v122, v208
	v_mul_f32_e32 v123, v123, v209
	v_mul_f32_e32 v124, v210, v124
	v_mul_f32_e32 v125, v210, v125
	v_mul_f32_e32 v126, v210, v126
	v_mul_f32_e32 v127, v210, v127
	v_mul_f32_e32 v120, v210, v120
	v_mul_f32_e32 v121, v210, v121
	v_mul_f32_e32 v122, v210, v122
	v_mul_f32_e32 v123, v210, v123
	v_cvt_pk_bf16_f32 v124, v124, v125
	v_cvt_pk_bf16_f32 v125, v126, v127
	v_cvt_pk_bf16_f32 v126, v120, v121
	v_cvt_pk_bf16_f32 v127, v122, v123
	global_store_dwordx4 v[128:129], v[124:127], off offset:256
	v_lshl_add_u64 v[128:129], v[128:129], 0, s[100:101]
	v_mul_f32_e32 v52, v52, v170
	v_mul_f32_e32 v53, v53, v170
	v_mul_f32_e32 v54, v54, v170
	v_mul_f32_e32 v55, v55, v170
	v_mul_f32_e32 v48, v48, v170
	v_mul_f32_e32 v49, v49, v170
	v_mul_f32_e32 v50, v50, v170
	v_mul_f32_e32 v51, v51, v170
	v_mul_f32_e32 v202, 0xbfb8aa3b, v52
	v_mul_f32_e32 v203, 0xbfb8aa3b, v53
	v_mul_f32_e32 v204, 0xbfb8aa3b, v54
	v_mul_f32_e32 v205, 0xbfb8aa3b, v55
	v_mul_f32_e32 v206, 0xbfb8aa3b, v48
	v_mul_f32_e32 v207, 0xbfb8aa3b, v49
	v_mul_f32_e32 v208, 0xbfb8aa3b, v50
	v_mul_f32_e32 v209, 0xbfb8aa3b, v51
	v_exp_f32_e32 v202, v202
	v_exp_f32_e32 v203, v203
	v_exp_f32_e32 v204, v204
	v_exp_f32_e32 v205, v205
	v_exp_f32_e32 v206, v206
	v_exp_f32_e32 v207, v207
	v_exp_f32_e32 v208, v208
	v_exp_f32_e32 v209, v209
	v_add_f32_e32 v202, 1.0, v202
	v_add_f32_e32 v203, 1.0, v203
	v_add_f32_e32 v204, 1.0, v204
	v_add_f32_e32 v205, 1.0, v205
	v_add_f32_e32 v206, 1.0, v206
	v_add_f32_e32 v207, 1.0, v207
	v_add_f32_e32 v208, 1.0, v208
	v_add_f32_e32 v209, 1.0, v209
	v_rcp_f32_e32 v202, v202
	v_rcp_f32_e32 v203, v203
	v_rcp_f32_e32 v204, v204
	v_rcp_f32_e32 v205, v205
	v_rcp_f32_e32 v206, v206
	v_rcp_f32_e32 v207, v207
	v_rcp_f32_e32 v208, v208
	v_rcp_f32_e32 v209, v209
	v_mul_f32_e32 v52, v52, v202
	v_mul_f32_e32 v53, v53, v203
	v_mul_f32_e32 v54, v54, v204
	v_mul_f32_e32 v55, v55, v205
	v_mul_f32_e32 v48, v48, v206
	v_mul_f32_e32 v49, v49, v207
	v_mul_f32_e32 v50, v50, v208
	v_mul_f32_e32 v51, v51, v209
	v_mul_f32_e32 v52, v210, v52
	v_mul_f32_e32 v53, v210, v53
	v_mul_f32_e32 v54, v210, v54
	v_mul_f32_e32 v55, v210, v55
	v_mul_f32_e32 v48, v210, v48
	v_mul_f32_e32 v49, v210, v49
	v_mul_f32_e32 v50, v210, v50
	v_mul_f32_e32 v51, v210, v51
	v_cvt_pk_bf16_f32 v52, v52, v53
	v_cvt_pk_bf16_f32 v53, v54, v55
	v_cvt_pk_bf16_f32 v54, v48, v49
	v_cvt_pk_bf16_f32 v55, v50, v51
	global_store_dwordx4 v[128:129], v[52:55], off
	v_mul_f32_e32 v116, v116, v170
	v_mul_f32_e32 v117, v117, v170
	v_mul_f32_e32 v118, v118, v170
	v_mul_f32_e32 v119, v119, v170
	v_mul_f32_e32 v112, v112, v170
	v_mul_f32_e32 v113, v113, v170
	v_mul_f32_e32 v114, v114, v170
	v_mul_f32_e32 v115, v115, v170
	v_mul_f32_e32 v202, 0xbfb8aa3b, v116
	v_mul_f32_e32 v203, 0xbfb8aa3b, v117
	v_mul_f32_e32 v204, 0xbfb8aa3b, v118
	v_mul_f32_e32 v205, 0xbfb8aa3b, v119
	v_mul_f32_e32 v206, 0xbfb8aa3b, v112
	v_mul_f32_e32 v207, 0xbfb8aa3b, v113
	v_mul_f32_e32 v208, 0xbfb8aa3b, v114
	v_mul_f32_e32 v209, 0xbfb8aa3b, v115
	v_exp_f32_e32 v202, v202
	v_exp_f32_e32 v203, v203
	v_exp_f32_e32 v204, v204
	v_exp_f32_e32 v205, v205
	v_exp_f32_e32 v206, v206
	v_exp_f32_e32 v207, v207
	v_exp_f32_e32 v208, v208
	v_exp_f32_e32 v209, v209
	v_add_f32_e32 v202, 1.0, v202
	v_add_f32_e32 v203, 1.0, v203
	v_add_f32_e32 v204, 1.0, v204
	v_add_f32_e32 v205, 1.0, v205
	v_add_f32_e32 v206, 1.0, v206
	v_add_f32_e32 v207, 1.0, v207
	v_add_f32_e32 v208, 1.0, v208
	v_add_f32_e32 v209, 1.0, v209
	v_rcp_f32_e32 v202, v202
	v_rcp_f32_e32 v203, v203
	v_rcp_f32_e32 v204, v204
	v_rcp_f32_e32 v205, v205
	v_rcp_f32_e32 v206, v206
	v_rcp_f32_e32 v207, v207
	v_rcp_f32_e32 v208, v208
	v_rcp_f32_e32 v209, v209
	v_mul_f32_e32 v116, v116, v202
	v_mul_f32_e32 v117, v117, v203
	v_mul_f32_e32 v118, v118, v204
	v_mul_f32_e32 v119, v119, v205
	v_mul_f32_e32 v112, v112, v206
	v_mul_f32_e32 v113, v113, v207
	v_mul_f32_e32 v114, v114, v208
	v_mul_f32_e32 v115, v115, v209
	v_mul_f32_e32 v116, v210, v116
	v_mul_f32_e32 v117, v210, v117
	v_mul_f32_e32 v118, v210, v118
	v_mul_f32_e32 v119, v210, v119
	v_mul_f32_e32 v112, v210, v112
	v_mul_f32_e32 v113, v210, v113
	v_mul_f32_e32 v114, v210, v114
	v_mul_f32_e32 v115, v210, v115
	v_cvt_pk_bf16_f32 v116, v116, v117
	v_cvt_pk_bf16_f32 v117, v118, v119
	v_cvt_pk_bf16_f32 v118, v112, v113
	v_cvt_pk_bf16_f32 v119, v114, v115
	global_store_dwordx4 v[128:129], v[116:119], off offset:256
	v_lshl_add_u64 v[128:129], v[128:129], 0, s[100:101]
	v_mul_f32_e32 v44, v44, v168
	v_mul_f32_e32 v45, v45, v168
	v_mul_f32_e32 v46, v46, v168
	v_mul_f32_e32 v47, v47, v168
	v_mul_f32_e32 v40, v40, v168
	v_mul_f32_e32 v41, v41, v168
	v_mul_f32_e32 v42, v42, v168
	v_mul_f32_e32 v43, v43, v168
	v_mul_f32_e32 v202, 0xbfb8aa3b, v44
	v_mul_f32_e32 v203, 0xbfb8aa3b, v45
	v_mul_f32_e32 v204, 0xbfb8aa3b, v46
	v_mul_f32_e32 v205, 0xbfb8aa3b, v47
	v_mul_f32_e32 v206, 0xbfb8aa3b, v40
	v_mul_f32_e32 v207, 0xbfb8aa3b, v41
	v_mul_f32_e32 v208, 0xbfb8aa3b, v42
	v_mul_f32_e32 v209, 0xbfb8aa3b, v43
	v_exp_f32_e32 v202, v202
	v_exp_f32_e32 v203, v203
	v_exp_f32_e32 v204, v204
	v_exp_f32_e32 v205, v205
	v_exp_f32_e32 v206, v206
	v_exp_f32_e32 v207, v207
	v_exp_f32_e32 v208, v208
	v_exp_f32_e32 v209, v209
	v_add_f32_e32 v202, 1.0, v202
	v_add_f32_e32 v203, 1.0, v203
	v_add_f32_e32 v204, 1.0, v204
	v_add_f32_e32 v205, 1.0, v205
	v_add_f32_e32 v206, 1.0, v206
	v_add_f32_e32 v207, 1.0, v207
	v_add_f32_e32 v208, 1.0, v208
	v_add_f32_e32 v209, 1.0, v209
	v_rcp_f32_e32 v202, v202
	v_rcp_f32_e32 v203, v203
	v_rcp_f32_e32 v204, v204
	v_rcp_f32_e32 v205, v205
	v_rcp_f32_e32 v206, v206
	v_rcp_f32_e32 v207, v207
	v_rcp_f32_e32 v208, v208
	v_rcp_f32_e32 v209, v209
	v_mul_f32_e32 v44, v44, v202
	v_mul_f32_e32 v45, v45, v203
	v_mul_f32_e32 v46, v46, v204
	v_mul_f32_e32 v47, v47, v205
	v_mul_f32_e32 v40, v40, v206
	v_mul_f32_e32 v41, v41, v207
	v_mul_f32_e32 v42, v42, v208
	v_mul_f32_e32 v43, v43, v209
	v_mul_f32_e32 v44, v210, v44
	v_mul_f32_e32 v45, v210, v45
	v_mul_f32_e32 v46, v210, v46
	v_mul_f32_e32 v47, v210, v47
	v_mul_f32_e32 v40, v210, v40
	v_mul_f32_e32 v41, v210, v41
	v_mul_f32_e32 v42, v210, v42
	v_mul_f32_e32 v43, v210, v43
	v_cvt_pk_bf16_f32 v44, v44, v45
	v_cvt_pk_bf16_f32 v45, v46, v47
	v_cvt_pk_bf16_f32 v46, v40, v41
	v_cvt_pk_bf16_f32 v47, v42, v43
	global_store_dwordx4 v[128:129], v[44:47], off
	v_mul_f32_e32 v108, v108, v168
	v_mul_f32_e32 v109, v109, v168
	v_mul_f32_e32 v110, v110, v168
	v_mul_f32_e32 v111, v111, v168
	v_mul_f32_e32 v104, v104, v168
	v_mul_f32_e32 v105, v105, v168
	v_mul_f32_e32 v106, v106, v168
	v_mul_f32_e32 v107, v107, v168
	v_mul_f32_e32 v202, 0xbfb8aa3b, v108
	v_mul_f32_e32 v203, 0xbfb8aa3b, v109
	v_mul_f32_e32 v204, 0xbfb8aa3b, v110
	v_mul_f32_e32 v205, 0xbfb8aa3b, v111
	v_mul_f32_e32 v206, 0xbfb8aa3b, v104
	v_mul_f32_e32 v207, 0xbfb8aa3b, v105
	v_mul_f32_e32 v208, 0xbfb8aa3b, v106
	v_mul_f32_e32 v209, 0xbfb8aa3b, v107
	v_exp_f32_e32 v202, v202
	v_exp_f32_e32 v203, v203
	v_exp_f32_e32 v204, v204
	v_exp_f32_e32 v205, v205
	v_exp_f32_e32 v206, v206
	v_exp_f32_e32 v207, v207
	v_exp_f32_e32 v208, v208
	v_exp_f32_e32 v209, v209
	v_add_f32_e32 v202, 1.0, v202
	v_add_f32_e32 v203, 1.0, v203
	v_add_f32_e32 v204, 1.0, v204
	v_add_f32_e32 v205, 1.0, v205
	v_add_f32_e32 v206, 1.0, v206
	v_add_f32_e32 v207, 1.0, v207
	v_add_f32_e32 v208, 1.0, v208
	v_add_f32_e32 v209, 1.0, v209
	v_rcp_f32_e32 v202, v202
	v_rcp_f32_e32 v203, v203
	v_rcp_f32_e32 v204, v204
	v_rcp_f32_e32 v205, v205
	v_rcp_f32_e32 v206, v206
	v_rcp_f32_e32 v207, v207
	v_rcp_f32_e32 v208, v208
	v_rcp_f32_e32 v209, v209
	v_mul_f32_e32 v108, v108, v202
	v_mul_f32_e32 v109, v109, v203
	v_mul_f32_e32 v110, v110, v204
	v_mul_f32_e32 v111, v111, v205
	v_mul_f32_e32 v104, v104, v206
	v_mul_f32_e32 v105, v105, v207
	v_mul_f32_e32 v106, v106, v208
	v_mul_f32_e32 v107, v107, v209
	v_mul_f32_e32 v108, v210, v108
	v_mul_f32_e32 v109, v210, v109
	v_mul_f32_e32 v110, v210, v110
	v_mul_f32_e32 v111, v210, v111
	v_mul_f32_e32 v104, v210, v104
	v_mul_f32_e32 v105, v210, v105
	v_mul_f32_e32 v106, v210, v106
	v_mul_f32_e32 v107, v210, v107
	v_cvt_pk_bf16_f32 v108, v108, v109
	v_cvt_pk_bf16_f32 v109, v110, v111
	v_cvt_pk_bf16_f32 v110, v104, v105
	v_cvt_pk_bf16_f32 v111, v106, v107
	global_store_dwordx4 v[128:129], v[108:111], off offset:256
	v_lshl_add_u64 v[128:129], v[128:129], 0, s[100:101]
	v_mul_f32_e32 v36, v36, v166
	v_mul_f32_e32 v37, v37, v166
	v_mul_f32_e32 v38, v38, v166
	v_mul_f32_e32 v39, v39, v166
	v_mul_f32_e32 v32, v32, v166
	v_mul_f32_e32 v33, v33, v166
	v_mul_f32_e32 v34, v34, v166
	v_mul_f32_e32 v35, v35, v166
	v_mul_f32_e32 v202, 0xbfb8aa3b, v36
	v_mul_f32_e32 v203, 0xbfb8aa3b, v37
	v_mul_f32_e32 v204, 0xbfb8aa3b, v38
	v_mul_f32_e32 v205, 0xbfb8aa3b, v39
	v_mul_f32_e32 v206, 0xbfb8aa3b, v32
	v_mul_f32_e32 v207, 0xbfb8aa3b, v33
	v_mul_f32_e32 v208, 0xbfb8aa3b, v34
	v_mul_f32_e32 v209, 0xbfb8aa3b, v35
	v_exp_f32_e32 v202, v202
	v_exp_f32_e32 v203, v203
	v_exp_f32_e32 v204, v204
	v_exp_f32_e32 v205, v205
	v_exp_f32_e32 v206, v206
	v_exp_f32_e32 v207, v207
	v_exp_f32_e32 v208, v208
	v_exp_f32_e32 v209, v209
	v_add_f32_e32 v202, 1.0, v202
	v_add_f32_e32 v203, 1.0, v203
	v_add_f32_e32 v204, 1.0, v204
	v_add_f32_e32 v205, 1.0, v205
	v_add_f32_e32 v206, 1.0, v206
	v_add_f32_e32 v207, 1.0, v207
	v_add_f32_e32 v208, 1.0, v208
	v_add_f32_e32 v209, 1.0, v209
	v_rcp_f32_e32 v202, v202
	v_rcp_f32_e32 v203, v203
	v_rcp_f32_e32 v204, v204
	v_rcp_f32_e32 v205, v205
	v_rcp_f32_e32 v206, v206
	v_rcp_f32_e32 v207, v207
	v_rcp_f32_e32 v208, v208
	v_rcp_f32_e32 v209, v209
	v_mul_f32_e32 v36, v36, v202
	v_mul_f32_e32 v37, v37, v203
	v_mul_f32_e32 v38, v38, v204
	v_mul_f32_e32 v39, v39, v205
	v_mul_f32_e32 v32, v32, v206
	v_mul_f32_e32 v33, v33, v207
	v_mul_f32_e32 v34, v34, v208
	v_mul_f32_e32 v35, v35, v209
	v_mul_f32_e32 v36, v210, v36
	v_mul_f32_e32 v37, v210, v37
	v_mul_f32_e32 v38, v210, v38
	v_mul_f32_e32 v39, v210, v39
	v_mul_f32_e32 v32, v210, v32
	v_mul_f32_e32 v33, v210, v33
	v_mul_f32_e32 v34, v210, v34
	v_mul_f32_e32 v35, v210, v35
	v_cvt_pk_bf16_f32 v36, v36, v37
	v_cvt_pk_bf16_f32 v37, v38, v39
	v_cvt_pk_bf16_f32 v38, v32, v33
	v_cvt_pk_bf16_f32 v39, v34, v35
	global_store_dwordx4 v[128:129], v[36:39], off
	v_mul_f32_e32 v100, v100, v166
	v_mul_f32_e32 v101, v101, v166
	v_mul_f32_e32 v102, v102, v166
	v_mul_f32_e32 v103, v103, v166
	v_mul_f32_e32 v96, v96, v166
	v_mul_f32_e32 v97, v97, v166
	v_mul_f32_e32 v98, v98, v166
	v_mul_f32_e32 v99, v99, v166
	v_mul_f32_e32 v202, 0xbfb8aa3b, v100
	v_mul_f32_e32 v203, 0xbfb8aa3b, v101
	v_mul_f32_e32 v204, 0xbfb8aa3b, v102
	v_mul_f32_e32 v205, 0xbfb8aa3b, v103
	v_mul_f32_e32 v206, 0xbfb8aa3b, v96
	v_mul_f32_e32 v207, 0xbfb8aa3b, v97
	v_mul_f32_e32 v208, 0xbfb8aa3b, v98
	v_mul_f32_e32 v209, 0xbfb8aa3b, v99
	v_exp_f32_e32 v202, v202
	v_exp_f32_e32 v203, v203
	v_exp_f32_e32 v204, v204
	v_exp_f32_e32 v205, v205
	v_exp_f32_e32 v206, v206
	v_exp_f32_e32 v207, v207
	v_exp_f32_e32 v208, v208
	v_exp_f32_e32 v209, v209
	v_add_f32_e32 v202, 1.0, v202
	v_add_f32_e32 v203, 1.0, v203
	v_add_f32_e32 v204, 1.0, v204
	v_add_f32_e32 v205, 1.0, v205
	v_add_f32_e32 v206, 1.0, v206
	v_add_f32_e32 v207, 1.0, v207
	v_add_f32_e32 v208, 1.0, v208
	v_add_f32_e32 v209, 1.0, v209
	v_rcp_f32_e32 v202, v202
	v_rcp_f32_e32 v203, v203
	v_rcp_f32_e32 v204, v204
	v_rcp_f32_e32 v205, v205
	v_rcp_f32_e32 v206, v206
	v_rcp_f32_e32 v207, v207
	v_rcp_f32_e32 v208, v208
	v_rcp_f32_e32 v209, v209
	v_mul_f32_e32 v100, v100, v202
	v_mul_f32_e32 v101, v101, v203
	v_mul_f32_e32 v102, v102, v204
	v_mul_f32_e32 v103, v103, v205
	v_mul_f32_e32 v96, v96, v206
	v_mul_f32_e32 v97, v97, v207
	v_mul_f32_e32 v98, v98, v208
	v_mul_f32_e32 v99, v99, v209
	v_mul_f32_e32 v100, v210, v100
	v_mul_f32_e32 v101, v210, v101
	v_mul_f32_e32 v102, v210, v102
	v_mul_f32_e32 v103, v210, v103
	v_mul_f32_e32 v96, v210, v96
	v_mul_f32_e32 v97, v210, v97
	v_mul_f32_e32 v98, v210, v98
	v_mul_f32_e32 v99, v210, v99
	v_cvt_pk_bf16_f32 v100, v100, v101
	v_cvt_pk_bf16_f32 v101, v102, v103
	v_cvt_pk_bf16_f32 v102, v96, v97
	v_cvt_pk_bf16_f32 v103, v98, v99
	global_store_dwordx4 v[128:129], v[100:103], off offset:256
	s_mov_b64 s[100:101], 0x96000
	v_lshl_add_u64 v[128:129], v[128:129], 0, s[100:101]
	s_mov_b64 s[100:101], 0x1e000
	v_mul_f32_e32 v28, v28, v162
	v_mul_f32_e32 v29, v29, v162
	v_mul_f32_e32 v30, v30, v162
	v_mul_f32_e32 v31, v31, v162
	v_mul_f32_e32 v24, v24, v162
	v_mul_f32_e32 v25, v25, v162
	v_mul_f32_e32 v26, v26, v162
	v_mul_f32_e32 v27, v27, v162
	v_mul_f32_e32 v202, 0xbfb8aa3b, v28
	v_mul_f32_e32 v203, 0xbfb8aa3b, v29
	v_mul_f32_e32 v204, 0xbfb8aa3b, v30
	v_mul_f32_e32 v205, 0xbfb8aa3b, v31
	v_mul_f32_e32 v206, 0xbfb8aa3b, v24
	v_mul_f32_e32 v207, 0xbfb8aa3b, v25
	v_mul_f32_e32 v208, 0xbfb8aa3b, v26
	v_mul_f32_e32 v209, 0xbfb8aa3b, v27
	v_exp_f32_e32 v202, v202
	v_exp_f32_e32 v203, v203
	v_exp_f32_e32 v204, v204
	v_exp_f32_e32 v205, v205
	v_exp_f32_e32 v206, v206
	v_exp_f32_e32 v207, v207
	v_exp_f32_e32 v208, v208
	v_exp_f32_e32 v209, v209
	v_add_f32_e32 v202, 1.0, v202
	v_add_f32_e32 v203, 1.0, v203
	v_add_f32_e32 v204, 1.0, v204
	v_add_f32_e32 v205, 1.0, v205
	v_add_f32_e32 v206, 1.0, v206
	v_add_f32_e32 v207, 1.0, v207
	v_add_f32_e32 v208, 1.0, v208
	v_add_f32_e32 v209, 1.0, v209
	v_rcp_f32_e32 v202, v202
	v_rcp_f32_e32 v203, v203
	v_rcp_f32_e32 v204, v204
	v_rcp_f32_e32 v205, v205
	v_rcp_f32_e32 v206, v206
	v_rcp_f32_e32 v207, v207
	v_rcp_f32_e32 v208, v208
	v_rcp_f32_e32 v209, v209
	v_mul_f32_e32 v28, v28, v202
	v_mul_f32_e32 v29, v29, v203
	v_mul_f32_e32 v30, v30, v204
	v_mul_f32_e32 v31, v31, v205
	v_mul_f32_e32 v24, v24, v206
	v_mul_f32_e32 v25, v25, v207
	v_mul_f32_e32 v26, v26, v208
	v_mul_f32_e32 v27, v27, v209
	v_mul_f32_e32 v28, v210, v28
	v_mul_f32_e32 v29, v210, v29
	v_mul_f32_e32 v30, v210, v30
	v_mul_f32_e32 v31, v210, v31
	v_mul_f32_e32 v24, v210, v24
	v_mul_f32_e32 v25, v210, v25
	v_mul_f32_e32 v26, v210, v26
	v_mul_f32_e32 v27, v210, v27
	v_cvt_pk_bf16_f32 v28, v28, v29
	v_cvt_pk_bf16_f32 v29, v30, v31
	v_cvt_pk_bf16_f32 v30, v24, v25
	v_cvt_pk_bf16_f32 v31, v26, v27
	global_store_dwordx4 v[128:129], v[28:31], off
	v_mul_f32_e32 v92, v92, v162
	v_mul_f32_e32 v93, v93, v162
	v_mul_f32_e32 v94, v94, v162
	v_mul_f32_e32 v95, v95, v162
	v_mul_f32_e32 v88, v88, v162
	v_mul_f32_e32 v89, v89, v162
	v_mul_f32_e32 v90, v90, v162
	v_mul_f32_e32 v91, v91, v162
	v_mul_f32_e32 v202, 0xbfb8aa3b, v92
	v_mul_f32_e32 v203, 0xbfb8aa3b, v93
	v_mul_f32_e32 v204, 0xbfb8aa3b, v94
	v_mul_f32_e32 v205, 0xbfb8aa3b, v95
	v_mul_f32_e32 v206, 0xbfb8aa3b, v88
	v_mul_f32_e32 v207, 0xbfb8aa3b, v89
	v_mul_f32_e32 v208, 0xbfb8aa3b, v90
	v_mul_f32_e32 v209, 0xbfb8aa3b, v91
	v_exp_f32_e32 v202, v202
	v_exp_f32_e32 v203, v203
	v_exp_f32_e32 v204, v204
	v_exp_f32_e32 v205, v205
	v_exp_f32_e32 v206, v206
	v_exp_f32_e32 v207, v207
	v_exp_f32_e32 v208, v208
	v_exp_f32_e32 v209, v209
	v_add_f32_e32 v202, 1.0, v202
	v_add_f32_e32 v203, 1.0, v203
	v_add_f32_e32 v204, 1.0, v204
	v_add_f32_e32 v205, 1.0, v205
	v_add_f32_e32 v206, 1.0, v206
	v_add_f32_e32 v207, 1.0, v207
	v_add_f32_e32 v208, 1.0, v208
	v_add_f32_e32 v209, 1.0, v209
	v_rcp_f32_e32 v202, v202
	v_rcp_f32_e32 v203, v203
	v_rcp_f32_e32 v204, v204
	v_rcp_f32_e32 v205, v205
	v_rcp_f32_e32 v206, v206
	v_rcp_f32_e32 v207, v207
	v_rcp_f32_e32 v208, v208
	v_rcp_f32_e32 v209, v209
	v_mul_f32_e32 v92, v92, v202
	v_mul_f32_e32 v93, v93, v203
	v_mul_f32_e32 v94, v94, v204
	v_mul_f32_e32 v95, v95, v205
	v_mul_f32_e32 v88, v88, v206
	v_mul_f32_e32 v89, v89, v207
	v_mul_f32_e32 v90, v90, v208
	v_mul_f32_e32 v91, v91, v209
	v_mul_f32_e32 v92, v210, v92
	v_mul_f32_e32 v93, v210, v93
	v_mul_f32_e32 v94, v210, v94
	v_mul_f32_e32 v95, v210, v95
	v_mul_f32_e32 v88, v210, v88
	v_mul_f32_e32 v89, v210, v89
	v_mul_f32_e32 v90, v210, v90
	v_mul_f32_e32 v91, v210, v91
	v_cvt_pk_bf16_f32 v92, v92, v93
	v_cvt_pk_bf16_f32 v93, v94, v95
	v_cvt_pk_bf16_f32 v94, v88, v89
	v_cvt_pk_bf16_f32 v95, v90, v91
	global_store_dwordx4 v[128:129], v[92:95], off offset:256
	v_lshl_add_u64 v[128:129], v[128:129], 0, s[100:101]
	v_mul_f32_e32 v20, v20, v160
	v_mul_f32_e32 v21, v21, v160
	v_mul_f32_e32 v22, v22, v160
	v_mul_f32_e32 v23, v23, v160
	v_mul_f32_e32 v16, v16, v160
	v_mul_f32_e32 v17, v17, v160
	v_mul_f32_e32 v18, v18, v160
	v_mul_f32_e32 v19, v19, v160
	v_mul_f32_e32 v202, 0xbfb8aa3b, v20
	v_mul_f32_e32 v203, 0xbfb8aa3b, v21
	v_mul_f32_e32 v204, 0xbfb8aa3b, v22
	v_mul_f32_e32 v205, 0xbfb8aa3b, v23
	v_mul_f32_e32 v206, 0xbfb8aa3b, v16
	v_mul_f32_e32 v207, 0xbfb8aa3b, v17
	v_mul_f32_e32 v208, 0xbfb8aa3b, v18
	v_mul_f32_e32 v209, 0xbfb8aa3b, v19
	v_exp_f32_e32 v202, v202
	v_exp_f32_e32 v203, v203
	v_exp_f32_e32 v204, v204
	v_exp_f32_e32 v205, v205
	v_exp_f32_e32 v206, v206
	v_exp_f32_e32 v207, v207
	v_exp_f32_e32 v208, v208
	v_exp_f32_e32 v209, v209
	v_add_f32_e32 v202, 1.0, v202
	v_add_f32_e32 v203, 1.0, v203
	v_add_f32_e32 v204, 1.0, v204
	v_add_f32_e32 v205, 1.0, v205
	v_add_f32_e32 v206, 1.0, v206
	v_add_f32_e32 v207, 1.0, v207
	v_add_f32_e32 v208, 1.0, v208
	v_add_f32_e32 v209, 1.0, v209
	v_rcp_f32_e32 v202, v202
	v_rcp_f32_e32 v203, v203
	v_rcp_f32_e32 v204, v204
	v_rcp_f32_e32 v205, v205
	v_rcp_f32_e32 v206, v206
	v_rcp_f32_e32 v207, v207
	v_rcp_f32_e32 v208, v208
	v_rcp_f32_e32 v209, v209
	v_mul_f32_e32 v20, v20, v202
	v_mul_f32_e32 v21, v21, v203
	v_mul_f32_e32 v22, v22, v204
	v_mul_f32_e32 v23, v23, v205
	v_mul_f32_e32 v16, v16, v206
	v_mul_f32_e32 v17, v17, v207
	v_mul_f32_e32 v18, v18, v208
	v_mul_f32_e32 v19, v19, v209
	v_mul_f32_e32 v20, v210, v20
	v_mul_f32_e32 v21, v210, v21
	v_mul_f32_e32 v22, v210, v22
	v_mul_f32_e32 v23, v210, v23
	v_mul_f32_e32 v16, v210, v16
	v_mul_f32_e32 v17, v210, v17
	v_mul_f32_e32 v18, v210, v18
	v_mul_f32_e32 v19, v210, v19
	v_cvt_pk_bf16_f32 v20, v20, v21
	v_cvt_pk_bf16_f32 v21, v22, v23
	v_cvt_pk_bf16_f32 v22, v16, v17
	v_cvt_pk_bf16_f32 v23, v18, v19
	global_store_dwordx4 v[128:129], v[20:23], off
	v_mul_f32_e32 v84, v84, v160
	v_mul_f32_e32 v85, v85, v160
	v_mul_f32_e32 v86, v86, v160
	v_mul_f32_e32 v87, v87, v160
	v_mul_f32_e32 v80, v80, v160
	v_mul_f32_e32 v81, v81, v160
	v_mul_f32_e32 v82, v82, v160
	v_mul_f32_e32 v83, v83, v160
	v_mul_f32_e32 v202, 0xbfb8aa3b, v84
	v_mul_f32_e32 v203, 0xbfb8aa3b, v85
	v_mul_f32_e32 v204, 0xbfb8aa3b, v86
	v_mul_f32_e32 v205, 0xbfb8aa3b, v87
	v_mul_f32_e32 v206, 0xbfb8aa3b, v80
	v_mul_f32_e32 v207, 0xbfb8aa3b, v81
	v_mul_f32_e32 v208, 0xbfb8aa3b, v82
	v_mul_f32_e32 v209, 0xbfb8aa3b, v83
	v_exp_f32_e32 v202, v202
	v_exp_f32_e32 v203, v203
	v_exp_f32_e32 v204, v204
	v_exp_f32_e32 v205, v205
	v_exp_f32_e32 v206, v206
	v_exp_f32_e32 v207, v207
	v_exp_f32_e32 v208, v208
	v_exp_f32_e32 v209, v209
	v_add_f32_e32 v202, 1.0, v202
	v_add_f32_e32 v203, 1.0, v203
	v_add_f32_e32 v204, 1.0, v204
	v_add_f32_e32 v205, 1.0, v205
	v_add_f32_e32 v206, 1.0, v206
	v_add_f32_e32 v207, 1.0, v207
	v_add_f32_e32 v208, 1.0, v208
	v_add_f32_e32 v209, 1.0, v209
	v_rcp_f32_e32 v202, v202
	v_rcp_f32_e32 v203, v203
	v_rcp_f32_e32 v204, v204
	v_rcp_f32_e32 v205, v205
	v_rcp_f32_e32 v206, v206
	v_rcp_f32_e32 v207, v207
	v_rcp_f32_e32 v208, v208
	v_rcp_f32_e32 v209, v209
	v_mul_f32_e32 v84, v84, v202
	v_mul_f32_e32 v85, v85, v203
	v_mul_f32_e32 v86, v86, v204
	v_mul_f32_e32 v87, v87, v205
	v_mul_f32_e32 v80, v80, v206
	v_mul_f32_e32 v81, v81, v207
	v_mul_f32_e32 v82, v82, v208
	v_mul_f32_e32 v83, v83, v209
	v_mul_f32_e32 v84, v210, v84
	v_mul_f32_e32 v85, v210, v85
	v_mul_f32_e32 v86, v210, v86
	v_mul_f32_e32 v87, v210, v87
	v_mul_f32_e32 v80, v210, v80
	v_mul_f32_e32 v81, v210, v81
	v_mul_f32_e32 v82, v210, v82
	v_mul_f32_e32 v83, v210, v83
	v_cvt_pk_bf16_f32 v84, v84, v85
	v_cvt_pk_bf16_f32 v85, v86, v87
	v_cvt_pk_bf16_f32 v86, v80, v81
	v_cvt_pk_bf16_f32 v87, v82, v83
	global_store_dwordx4 v[128:129], v[84:87], off offset:256
	v_lshl_add_u64 v[128:129], v[128:129], 0, s[100:101]
	v_mul_f32_e32 v12, v12, v158
	v_mul_f32_e32 v13, v13, v158
	v_mul_f32_e32 v14, v14, v158
	v_mul_f32_e32 v15, v15, v158
	v_mul_f32_e32 v8, v8, v158
	v_mul_f32_e32 v9, v9, v158
	v_mul_f32_e32 v10, v10, v158
	v_mul_f32_e32 v11, v11, v158
	v_mul_f32_e32 v202, 0xbfb8aa3b, v12
	v_mul_f32_e32 v203, 0xbfb8aa3b, v13
	v_mul_f32_e32 v204, 0xbfb8aa3b, v14
	v_mul_f32_e32 v205, 0xbfb8aa3b, v15
	v_mul_f32_e32 v206, 0xbfb8aa3b, v8
	v_mul_f32_e32 v207, 0xbfb8aa3b, v9
	v_mul_f32_e32 v208, 0xbfb8aa3b, v10
	v_mul_f32_e32 v209, 0xbfb8aa3b, v11
	v_exp_f32_e32 v202, v202
	v_exp_f32_e32 v203, v203
	v_exp_f32_e32 v204, v204
	v_exp_f32_e32 v205, v205
	v_exp_f32_e32 v206, v206
	v_exp_f32_e32 v207, v207
	v_exp_f32_e32 v208, v208
	v_exp_f32_e32 v209, v209
	v_add_f32_e32 v202, 1.0, v202
	v_add_f32_e32 v203, 1.0, v203
	v_add_f32_e32 v204, 1.0, v204
	v_add_f32_e32 v205, 1.0, v205
	v_add_f32_e32 v206, 1.0, v206
	v_add_f32_e32 v207, 1.0, v207
	v_add_f32_e32 v208, 1.0, v208
	v_add_f32_e32 v209, 1.0, v209
	v_rcp_f32_e32 v202, v202
	v_rcp_f32_e32 v203, v203
	v_rcp_f32_e32 v204, v204
	v_rcp_f32_e32 v205, v205
	v_rcp_f32_e32 v206, v206
	v_rcp_f32_e32 v207, v207
	v_rcp_f32_e32 v208, v208
	v_rcp_f32_e32 v209, v209
	v_mul_f32_e32 v12, v12, v202
	v_mul_f32_e32 v13, v13, v203
	v_mul_f32_e32 v14, v14, v204
	v_mul_f32_e32 v15, v15, v205
	v_mul_f32_e32 v8, v8, v206
	v_mul_f32_e32 v9, v9, v207
	v_mul_f32_e32 v10, v10, v208
	v_mul_f32_e32 v11, v11, v209
	v_mul_f32_e32 v12, v210, v12
	v_mul_f32_e32 v13, v210, v13
	v_mul_f32_e32 v14, v210, v14
	v_mul_f32_e32 v15, v210, v15
	v_mul_f32_e32 v8, v210, v8
	v_mul_f32_e32 v9, v210, v9
	v_mul_f32_e32 v10, v210, v10
	v_mul_f32_e32 v11, v210, v11
	v_cvt_pk_bf16_f32 v12, v12, v13
	v_cvt_pk_bf16_f32 v13, v14, v15
	v_cvt_pk_bf16_f32 v14, v8, v9
	v_cvt_pk_bf16_f32 v15, v10, v11
	global_store_dwordx4 v[128:129], v[12:15], off
	v_mul_f32_e32 v76, v76, v158
	v_mul_f32_e32 v77, v77, v158
	v_mul_f32_e32 v78, v78, v158
	v_mul_f32_e32 v79, v79, v158
	v_mul_f32_e32 v72, v72, v158
	v_mul_f32_e32 v73, v73, v158
	v_mul_f32_e32 v74, v74, v158
	v_mul_f32_e32 v75, v75, v158
	v_mul_f32_e32 v202, 0xbfb8aa3b, v76
	v_mul_f32_e32 v203, 0xbfb8aa3b, v77
	v_mul_f32_e32 v204, 0xbfb8aa3b, v78
	v_mul_f32_e32 v205, 0xbfb8aa3b, v79
	v_mul_f32_e32 v206, 0xbfb8aa3b, v72
	v_mul_f32_e32 v207, 0xbfb8aa3b, v73
	v_mul_f32_e32 v208, 0xbfb8aa3b, v74
	v_mul_f32_e32 v209, 0xbfb8aa3b, v75
	v_exp_f32_e32 v202, v202
	v_exp_f32_e32 v203, v203
	v_exp_f32_e32 v204, v204
	v_exp_f32_e32 v205, v205
	v_exp_f32_e32 v206, v206
	v_exp_f32_e32 v207, v207
	v_exp_f32_e32 v208, v208
	v_exp_f32_e32 v209, v209
	v_add_f32_e32 v202, 1.0, v202
	v_add_f32_e32 v203, 1.0, v203
	v_add_f32_e32 v204, 1.0, v204
	v_add_f32_e32 v205, 1.0, v205
	v_add_f32_e32 v206, 1.0, v206
	v_add_f32_e32 v207, 1.0, v207
	v_add_f32_e32 v208, 1.0, v208
	v_add_f32_e32 v209, 1.0, v209
	v_rcp_f32_e32 v202, v202
	v_rcp_f32_e32 v203, v203
	v_rcp_f32_e32 v204, v204
	v_rcp_f32_e32 v205, v205
	v_rcp_f32_e32 v206, v206
	v_rcp_f32_e32 v207, v207
	v_rcp_f32_e32 v208, v208
	v_rcp_f32_e32 v209, v209
	v_mul_f32_e32 v76, v76, v202
	v_mul_f32_e32 v77, v77, v203
	v_mul_f32_e32 v78, v78, v204
	v_mul_f32_e32 v79, v79, v205
	v_mul_f32_e32 v72, v72, v206
	v_mul_f32_e32 v73, v73, v207
	v_mul_f32_e32 v74, v74, v208
	v_mul_f32_e32 v75, v75, v209
	v_mul_f32_e32 v76, v210, v76
	v_mul_f32_e32 v77, v210, v77
	v_mul_f32_e32 v78, v210, v78
	v_mul_f32_e32 v79, v210, v79
	v_mul_f32_e32 v72, v210, v72
	v_mul_f32_e32 v73, v210, v73
	v_mul_f32_e32 v74, v210, v74
	v_mul_f32_e32 v75, v210, v75
	v_cvt_pk_bf16_f32 v76, v76, v77
	v_cvt_pk_bf16_f32 v77, v78, v79
	v_cvt_pk_bf16_f32 v78, v72, v73
	v_cvt_pk_bf16_f32 v79, v74, v75
	global_store_dwordx4 v[128:129], v[76:79], off offset:256
	v_lshl_add_u64 v[128:129], v[128:129], 0, s[100:101]
	v_mul_f32_e32 v4, v4, v156
	v_mul_f32_e32 v5, v5, v156
	v_mul_f32_e32 v6, v6, v156
	v_mul_f32_e32 v7, v7, v156
	v_mul_f32_e32 v0, v0, v156
	v_mul_f32_e32 v1, v1, v156
	v_mul_f32_e32 v2, v2, v156
	v_mul_f32_e32 v3, v3, v156
	v_mul_f32_e32 v202, 0xbfb8aa3b, v4
	v_mul_f32_e32 v203, 0xbfb8aa3b, v5
	v_mul_f32_e32 v204, 0xbfb8aa3b, v6
	v_mul_f32_e32 v205, 0xbfb8aa3b, v7
	v_mul_f32_e32 v206, 0xbfb8aa3b, v0
	v_mul_f32_e32 v207, 0xbfb8aa3b, v1
	v_mul_f32_e32 v208, 0xbfb8aa3b, v2
	v_mul_f32_e32 v209, 0xbfb8aa3b, v3
	v_exp_f32_e32 v202, v202
	v_exp_f32_e32 v203, v203
	v_exp_f32_e32 v204, v204
	v_exp_f32_e32 v205, v205
	v_exp_f32_e32 v206, v206
	v_exp_f32_e32 v207, v207
	v_exp_f32_e32 v208, v208
	v_exp_f32_e32 v209, v209
	v_add_f32_e32 v202, 1.0, v202
	v_add_f32_e32 v203, 1.0, v203
	v_add_f32_e32 v204, 1.0, v204
	v_add_f32_e32 v205, 1.0, v205
	v_add_f32_e32 v206, 1.0, v206
	v_add_f32_e32 v207, 1.0, v207
	v_add_f32_e32 v208, 1.0, v208
	v_add_f32_e32 v209, 1.0, v209
	v_rcp_f32_e32 v202, v202
	v_rcp_f32_e32 v203, v203
	v_rcp_f32_e32 v204, v204
	v_rcp_f32_e32 v205, v205
	v_rcp_f32_e32 v206, v206
	v_rcp_f32_e32 v207, v207
	v_rcp_f32_e32 v208, v208
	v_rcp_f32_e32 v209, v209
	v_mul_f32_e32 v4, v4, v202
	v_mul_f32_e32 v5, v5, v203
	v_mul_f32_e32 v6, v6, v204
	v_mul_f32_e32 v7, v7, v205
	v_mul_f32_e32 v0, v0, v206
	v_mul_f32_e32 v1, v1, v207
	v_mul_f32_e32 v2, v2, v208
	v_mul_f32_e32 v3, v3, v209
	v_mul_f32_e32 v4, v210, v4
	v_mul_f32_e32 v5, v210, v5
	v_mul_f32_e32 v6, v210, v6
	v_mul_f32_e32 v7, v210, v7
	v_mul_f32_e32 v0, v210, v0
	v_mul_f32_e32 v1, v210, v1
	v_mul_f32_e32 v2, v210, v2
	v_mul_f32_e32 v3, v210, v3
	v_cvt_pk_bf16_f32 v4, v4, v5
	v_cvt_pk_bf16_f32 v5, v6, v7
	v_cvt_pk_bf16_f32 v6, v0, v1
	v_cvt_pk_bf16_f32 v7, v2, v3
	global_store_dwordx4 v[128:129], v[4:7], off
	v_mul_f32_e32 v68, v68, v156
	v_mul_f32_e32 v69, v69, v156
	v_mul_f32_e32 v70, v70, v156
	v_mul_f32_e32 v71, v71, v156
	v_mul_f32_e32 v64, v64, v156
	v_mul_f32_e32 v65, v65, v156
	v_mul_f32_e32 v66, v66, v156
	v_mul_f32_e32 v67, v67, v156
	v_mul_f32_e32 v202, 0xbfb8aa3b, v68
	v_mul_f32_e32 v203, 0xbfb8aa3b, v69
	v_mul_f32_e32 v204, 0xbfb8aa3b, v70
	v_mul_f32_e32 v205, 0xbfb8aa3b, v71
	v_mul_f32_e32 v206, 0xbfb8aa3b, v64
	v_mul_f32_e32 v207, 0xbfb8aa3b, v65
	v_mul_f32_e32 v208, 0xbfb8aa3b, v66
	v_mul_f32_e32 v209, 0xbfb8aa3b, v67
	v_exp_f32_e32 v202, v202
	v_exp_f32_e32 v203, v203
	v_exp_f32_e32 v204, v204
	v_exp_f32_e32 v205, v205
	v_exp_f32_e32 v206, v206
	v_exp_f32_e32 v207, v207
	v_exp_f32_e32 v208, v208
	v_exp_f32_e32 v209, v209
	v_add_f32_e32 v202, 1.0, v202
	v_add_f32_e32 v203, 1.0, v203
	v_add_f32_e32 v204, 1.0, v204
	v_add_f32_e32 v205, 1.0, v205
	v_add_f32_e32 v206, 1.0, v206
	v_add_f32_e32 v207, 1.0, v207
	v_add_f32_e32 v208, 1.0, v208
	v_add_f32_e32 v209, 1.0, v209
	v_rcp_f32_e32 v202, v202
	v_rcp_f32_e32 v203, v203
	v_rcp_f32_e32 v204, v204
	v_rcp_f32_e32 v205, v205
	v_rcp_f32_e32 v206, v206
	v_rcp_f32_e32 v207, v207
	v_rcp_f32_e32 v208, v208
	v_rcp_f32_e32 v209, v209
	v_mul_f32_e32 v68, v68, v202
	v_mul_f32_e32 v69, v69, v203
	v_mul_f32_e32 v70, v70, v204
	v_mul_f32_e32 v71, v71, v205
	v_mul_f32_e32 v64, v64, v206
	v_mul_f32_e32 v65, v65, v207
	v_mul_f32_e32 v66, v66, v208
	v_mul_f32_e32 v67, v67, v209
	v_mul_f32_e32 v68, v210, v68
	v_mul_f32_e32 v69, v210, v69
	v_mul_f32_e32 v70, v210, v70
	v_mul_f32_e32 v71, v210, v71
	v_mul_f32_e32 v64, v210, v64
	v_mul_f32_e32 v65, v210, v65
	v_mul_f32_e32 v66, v210, v66
	v_mul_f32_e32 v67, v210, v67
	v_cvt_pk_bf16_f32 v68, v68, v69
	v_cvt_pk_bf16_f32 v69, v70, v71
	v_cvt_pk_bf16_f32 v70, v64, v65
	v_cvt_pk_bf16_f32 v71, v66, v67
	global_store_dwordx4 v[128:129], v[68:71], off offset:256
	s_branch .LBB0_271
